# deferred-prep table v10: the last 32 layer-1 fourier-fold items move from the L1 in-projection idle window (5 items on 32 workgroups) to the L0 in-projection idle window
# speedup vs baseline: 1.0082x; 1.0077x over previous
; __device__ void phase_prep(const Params& p, LAS unsigned char* lds) {
;     ...
;     constexpr int T_IN = 16 * 17, T_BA = 8 * 4, T_WO = 16 * 4, T_UP = 16 * 22, T_DN = 44 * 4, T_L = T_IN + T_BA + T_WO + T_UP + T_DN;
;     constexpr int I_TR = 2 * T_L, I_POOL = I_TR + 128, I_FOUR = I_POOL + 256, I_MOD = I_FOUR + 192, I_ALL = I_MOD + 1;
;     for (int prep_rep = 0; prep_rep < ((PROBE >= 301 && PROBE <= 304) ? 2 : 1); ++prep_rep)
;     for (int it = blockIdx.x; it < I_ALL; it += gridDim.x) {
;     ...
;         if (prep_rep == 1) { const int cls = (it < I_TR) ? 301 : (it < I_FOUR) ? 302 : (it < I_MOD) ? 303 : 304; if (cls != PROBE) continue; }
;     ...
;         if (it < I_TR) {
.Lmy_dp_m0:
	s_cmp_lt_u32 s26, 132
	s_cbranch_scc1 .LBB0_735
	s_sub_i32 s0, s26, 132
	v_writelane_b32 v252, s0, 1
	s_movk_i32 s1, 124
	v_writelane_b32 v252, s1, 2
	s_movk_i32 s1, 320
	v_writelane_b32 v252, s1, 3
	s_movk_i32 s1, 272
	v_writelane_b32 v252, s1, 0
	s_movk_i32 s1, 96
	v_writelane_b32 v252, s1, 5
	s_movk_i32 s1, 1696
	v_writelane_b32 v252, s1, 6
	s_movk_i32 s1, 160
	v_writelane_b32 v252, s1, 7
	s_movk_i32 s1, 1760
	v_writelane_b32 v252, s1, 8
	s_movk_i32 s1, 288
	v_writelane_b32 v252, s1, 9
	s_movk_i32 s1, 1856
	v_writelane_b32 v252, s1, 10
	s_branch .LBB0_650

; __device__ void phase_prep(const Params& p, LAS unsigned char* lds) {
;     ...
;     constexpr int T_IN = 16 * 17, T_BA = 8 * 4, T_WO = 16 * 4, T_UP = 16 * 22, T_DN = 44 * 4, T_L = T_IN + T_BA + T_WO + T_UP + T_DN;
;     constexpr int I_TR = 2 * T_L, I_POOL = I_TR + 128, I_FOUR = I_POOL + 256, I_MOD = I_FOUR + 192, I_ALL = I_MOD + 1;
;     for (int prep_rep = 0; prep_rep < ((PROBE >= 301 && PROBE <= 304) ? 2 : 1); ++prep_rep)
;     for (int it = blockIdx.x; it < I_ALL; it += gridDim.x) {
;     ...
;         if (prep_rep == 1) { const int cls = (it < I_TR) ? 301 : (it < I_FOUR) ? 302 : (it < I_MOD) ? 303 : 304; if (cls != PROBE) continue; }
;     ...
;         if (it < I_TR) {
.Lmy_dp_m2:
	s_cmp_lt_u32 s26, 84
	s_cbranch_scc1 .LBB0_735
	s_sub_i32 s0, s26, 84
	v_writelane_b32 v252, s0, 1
	s_movk_i32 s1, 172
	v_writelane_b32 v252, s1, 2
	s_movk_i32 s1, 688
	v_writelane_b32 v252, s1, 3
	s_movk_i32 s1, 1264
	v_writelane_b32 v252, s1, 0
	s_movk_i32 s1, 528
	v_writelane_b32 v252, s1, 5
	s_movk_i32 s1, 1328
	v_writelane_b32 v252, s1, 6
	s_movk_i32 s1, 592
	v_writelane_b32 v252, s1, 7
	s_movk_i32 s1, 1456
	v_writelane_b32 v252, s1, 8
	s_movk_i32 s1, 32767
	v_writelane_b32 v252, s1, 9
	s_movk_i32 s1, 0
	v_writelane_b32 v252, s1, 10
	s_branch .LBB0_650
